# attention hot loop row-max: 16 v_max3 instead of 53 VALU (hipcc canonicalising max tree)
# baseline (speedup 1.0000x reference)
; __device__ __forceinline__ void attn_tile(const LAS unsigned char* Kt, const LAS unsigned char* Vt, const LAS f32x4* ck, const bf16x8 (&qr)[4], const float cq2, const int kp0, const int qpos, const int qfirst, ...
;     ...
;             float rm = fmaxf(p0[0], p1[0]);
; #pragma unroll
;             for (int r = 1; r < 16; ++r) rm = fmaxf(rm, fmaxf(p0[r], p1[r]));
;             rm = fmaxf(rm, __shfl_xor(rm, 32));
;             if (first) { m_run = rm; cqm = cq2 - rm;
; #pragma unroll
;                 for (int r = 0; r < 16; ++r) { p0[r] -= rm; p1[r] -= rm; } }
;             else if (__any(rm > 8.f)) { const float dl = fmaxf(rm, 0.f), alpha = __builtin_amdgcn_exp2f(-dl); m_run += dl; cqm -= dl; l_run *= alpha;
; #pragma unroll
;                 for (int r = 0; r < 16; ++r) { p0[r] -= dl; p1[r] -= dl; o0[r] *= alpha; o1[r] *= alpha; } }
.LBB0_475:
	s_nop 10
	v_max3_f32 v1, v34, v35, v36
	v_max3_f32 v1, v1, v37, v38
	v_max3_f32 v1, v1, v39, v40
	v_max3_f32 v1, v1, v41, v42
	v_max3_f32 v1, v1, v43, v44
	v_max3_f32 v1, v1, v45, v46
	v_max3_f32 v1, v1, v47, v48
	v_max3_f32 v185, v50, v51, v52
	v_max3_f32 v185, v185, v53, v54
	v_max3_f32 v185, v185, v55, v56
	v_max3_f32 v185, v185, v57, v58
	v_max3_f32 v185, v185, v59, v60
	v_max3_f32 v185, v185, v61, v62
	v_max3_f32 v185, v185, v63, v64
	v_max3_f32 v1, v1, v185, v49
	v_max_f32_e32 v1, v1, v65
	v_and_b32_e32 v186, 64, v138
	v_xor_b32_e32 v185, 32, v138
	v_add_u32_e32 v186, 64, v186
	v_cmp_lt_i32_e64 s[0:1], v185, v186
	s_nop 1
	v_cndmask_b32_e64 v185, v138, v185, s[0:1]
	v_lshlrev_b32_e32 v185, 2, v185
	ds_bpermute_b32 v185, v185, v1
	s_waitcnt lgkmcnt(0)
	v_max_f32_e32 v185, v185, v185
	v_max_f32_e32 v1, v1, v185
	s_and_saveexec_b64 s[0:1], vcc
	s_xor_b64 s[0:1], exec, s[0:1]
	s_cbranch_execz .LBB0_479
	s_mov_b32 s10, 0x41000000
	v_cmp_lt_f32_e32 vcc, s10, v1
	s_cbranch_vccz .LBB0_478
	v_max_f32_e32 v1, v1, v1
	v_max_f32_e32 v1, 0, v1
	v_exp_f32_e64 v186, -v1
	v_add_f32_e32 v139, v139, v1
	v_sub_f32_e32 v184, v184, v1
	v_sub_f32_e32 v49, v49, v1
	v_mul_f32_e32 v118, v118, v186
	v_sub_f32_e32 v48, v48, v1
	v_sub_f32_e32 v47, v47, v1
	v_sub_f32_e32 v46, v46, v1
	v_sub_f32_e32 v45, v45, v1
	v_sub_f32_e32 v44, v44, v1
	v_sub_f32_e32 v43, v43, v1
	v_sub_f32_e32 v42, v42, v1
	v_sub_f32_e32 v41, v41, v1
	v_sub_f32_e32 v40, v40, v1
	v_sub_f32_e32 v39, v39, v1
	v_sub_f32_e32 v38, v38, v1
	v_sub_f32_e32 v37, v37, v1
	v_sub_f32_e32 v36, v36, v1
	v_sub_f32_e32 v35, v35, v1
	v_sub_f32_e32 v34, v34, v1
	v_sub_f32_e32 v65, v65, v1
	v_sub_f32_e32 v64, v64, v1
	v_sub_f32_e32 v63, v63, v1
	v_sub_f32_e32 v62, v62, v1
	v_sub_f32_e32 v61, v61, v1
	v_sub_f32_e32 v60, v60, v1
	v_sub_f32_e32 v59, v59, v1
	v_sub_f32_e32 v58, v58, v1
	v_sub_f32_e32 v57, v57, v1
	v_sub_f32_e32 v56, v56, v1
	v_sub_f32_e32 v55, v55, v1
	v_sub_f32_e32 v54, v54, v1
	v_sub_f32_e32 v53, v53, v1
	v_sub_f32_e32 v52, v52, v1
	v_sub_f32_e32 v51, v51, v1
	v_sub_f32_e32 v50, v50, v1
	v_pk_mul_f32 v[32:33], v[32:33], v[186:187] op_sel_hi:[1,0]
	v_pk_mul_f32 v[30:31], v[30:31], v[186:187] op_sel_hi:[1,0]
	v_pk_mul_f32 v[28:29], v[28:29], v[186:187] op_sel_hi:[1,0]
	v_pk_mul_f32 v[26:27], v[26:27], v[186:187] op_sel_hi:[1,0]
	v_pk_mul_f32 v[24:25], v[24:25], v[186:187] op_sel_hi:[1,0]
	v_pk_mul_f32 v[22:23], v[22:23], v[186:187] op_sel_hi:[1,0]
	v_pk_mul_f32 v[20:21], v[20:21], v[186:187] op_sel_hi:[1,0]
	v_pk_mul_f32 v[18:19], v[18:19], v[186:187] op_sel_hi:[1,0]
	v_pk_mul_f32 v[16:17], v[16:17], v[186:187] op_sel_hi:[1,0]
	v_pk_mul_f32 v[14:15], v[14:15], v[186:187] op_sel_hi:[1,0]
	v_pk_mul_f32 v[12:13], v[12:13], v[186:187] op_sel_hi:[1,0]
	v_pk_mul_f32 v[10:11], v[10:11], v[186:187] op_sel_hi:[1,0]
	v_pk_mul_f32 v[8:9], v[8:9], v[186:187] op_sel_hi:[1,0]
	v_pk_mul_f32 v[6:7], v[6:7], v[186:187] op_sel_hi:[1,0]
	v_pk_mul_f32 v[4:5], v[4:5], v[186:187] op_sel_hi:[1,0]
	v_pk_mul_f32 v[2:3], v[2:3], v[186:187] op_sel_hi:[1,0]
